# P4 and P6 epilogues: residual loads software-pipelined (8 in flight, counted waits) instead of one round trip per block
# baseline (speedup 1.0000x reference)
.LBB0_968:
	v_lshl_add_u32 v146, s22, 8, v148
	v_lshl_or_b32 v144, s24, 8, v150
	v_ashrrev_i32_e32 v147, 31, v146
	v_ashrrev_i32_e32 v145, 31, v144
	v_lshlrev_b64 v[156:157], 10, v[146:147]
	v_readlane_b32 s56, v246, 4
	v_lshl_add_u64 v[164:165], v[156:157], 0, v[144:145]
	v_readlane_b32 s57, v246, 5
	v_readlane_b32 s2, v246, 30
	v_readlane_b32 s3, v246, 31
	v_lshl_add_u64 v[166:167], v[164:165], 2, s[56:57]
	v_mov_b32_e32 v252, v166
	v_mov_b32_e32 v253, v167
	s_mov_b64 s[96:97], 0x10000
	global_load_dwordx4 v[172:175], v[252:253], off
	global_load_dwordx4 v[176:179], v[252:253], off offset:16
	global_load_dwordx4 v[180:183], v[252:253], off offset:512
	global_load_dwordx4 v[184:187], v[252:253], off offset:528
	v_lshl_add_u64 v[252:253], v[252:253], 0, s[96:97]
	global_load_dwordx4 v[188:191], v[252:253], off
	global_load_dwordx4 v[192:195], v[252:253], off offset:16
	global_load_dwordx4 v[196:199], v[252:253], off offset:512
	global_load_dwordx4 v[200:203], v[252:253], off offset:528
	v_lshl_add_u64 v[252:253], v[252:253], 0, s[96:97]
	s_nop 1
	s_nop 1
	v_lshlrev_b64 v[164:165], 1, v[164:165]
	v_lshl_add_u64 v[168:169], s[2:3], 0, v[164:165]
	v_xor_b32_e32 v155, 32, v154
	v_or_b32_e32 v164, 0x100, v164
	v_readlane_b32 s58, v246, 6
	v_readlane_b32 s59, v246, 7
	v_readlane_b32 s60, v246, 8
	v_readlane_b32 s61, v246, 9
	v_readlane_b32 s62, v246, 10
	v_readlane_b32 s63, v246, 11
	v_readlane_b32 s64, v246, 12
	v_readlane_b32 s65, v246, 13
	v_readlane_b32 s66, v246, 14
	v_readlane_b32 s67, v246, 15
	v_readlane_b32 s68, v246, 16
	v_readlane_b32 s69, v246, 17
	v_readlane_b32 s70, v246, 18
	v_readlane_b32 s71, v246, 19
	s_waitcnt vmcnt(6)
	v_mov_b32_e32 v156, v172
	v_mov_b32_e32 v157, v173
	v_mov_b32_e32 v158, v174
	v_mov_b32_e32 v159, v175
	v_mov_b32_e32 v160, v176
	v_mov_b32_e32 v161, v177
	v_mov_b32_e32 v162, v178
	v_mov_b32_e32 v163, v179
	global_load_dwordx4 v[172:175], v[252:253], off
	global_load_dwordx4 v[176:179], v[252:253], off offset:16
	v_pk_add_f32 v[126:127], v[126:127], v[158:159]
	v_pk_add_f32 v[170:171], v[124:125], v[156:157]
	v_pk_add_f32 v[162:163], v[122:123], v[162:163]
	v_pk_add_f32 v[160:161], v[120:121], v[160:161]
	v_cvt_pk_bf16_f32 v120, v170, v171
	v_cvt_pk_bf16_f32 v121, v126, v127
	v_mul_f32_e32 v127, v127, v127
	v_cvt_pk_bf16_f32 v122, v160, v161
	v_cvt_pk_bf16_f32 v123, v162, v163
	global_store_dwordx4 v[168:169], v[120:123], off
	s_nop 1
	s_nop 0
	s_nop 1
	v_mul_f32_e32 v166, v171, v171
	v_and_b32_e32 v121, 64, v154
	v_mul_f32_e32 v161, v161, v161
	v_fmac_f32_e32 v166, v170, v170
	v_fmac_f32_e32 v127, v126, v126
	v_xor_b32_e32 v120, 16, v154
	v_add_u32_e32 v121, 64, v121
	v_mul_f32_e32 v163, v163, v163
	v_fmac_f32_e32 v161, v160, v160
	v_add_f32_e32 v126, v166, v127
	v_cmp_lt_i32_e32 vcc, v120, v121
	v_fmac_f32_e32 v163, v162, v162
	v_add_f32_e32 v126, v126, v161
	v_cndmask_b32_e32 v120, v154, v120, vcc
	v_add_f32_e32 v126, v163, v126
	v_lshlrev_b32_e32 v120, 2, v120
	v_cmp_lt_i32_e32 vcc, v155, v121
	s_waitcnt vmcnt(7)
	v_mov_b32_e32 v122, v180
	v_mov_b32_e32 v123, v181
	v_mov_b32_e32 v124, v182
	v_mov_b32_e32 v125, v183
	v_mov_b32_e32 v156, v184
	v_mov_b32_e32 v157, v185
	v_mov_b32_e32 v158, v186
	v_mov_b32_e32 v159, v187
	global_load_dwordx4 v[180:183], v[252:253], off offset:512
	global_load_dwordx4 v[184:187], v[252:253], off offset:528
	s_mov_b64 s[96:97], 0x10000
	v_lshl_add_u64 v[252:253], v[252:253], 0, s[96:97]
	v_pk_add_f32 v[118:119], v[118:119], v[124:125]
	v_pk_add_f32 v[116:117], v[116:117], v[122:123]
	v_pk_add_f32 v[122:123], v[114:115], v[158:159]
	v_pk_add_f32 v[112:113], v[112:113], v[156:157]
	v_mul_f32_e32 v114, v117, v117
	v_mul_f32_e32 v115, v119, v119
	v_mul_f32_e32 v124, v113, v113
	v_fmac_f32_e32 v114, v116, v116
	v_fmac_f32_e32 v115, v118, v118
	v_mul_f32_e32 v125, v123, v123
	v_fmac_f32_e32 v124, v112, v112
	v_add_f32_e32 v114, v114, v115
	v_fmac_f32_e32 v125, v122, v122
	v_add_f32_e32 v114, v114, v124
	v_add_f32_e32 v114, v125, v114
	v_add_f32_e32 v114, v126, v114
	ds_bpermute_b32 v115, v120, v114
	v_cndmask_b32_e32 v121, v154, v155, vcc
	v_cvt_pk_bf16_f32 v116, v116, v117
	v_cvt_pk_bf16_f32 v117, v118, v119
	v_cvt_pk_bf16_f32 v118, v112, v113
	s_waitcnt lgkmcnt(0)
	v_add_f32_e32 v112, v114, v115
	v_lshlrev_b32_e32 v114, 2, v121
	ds_bpermute_b32 v113, v114, v112
	v_cvt_pk_bf16_f32 v119, v122, v123
	v_lshl_add_u64 v[122:123], s[2:3], 0, v[164:165]
	global_store_dwordx4 v[122:123], v[116:119], off
	s_and_saveexec_b64 s[2:3], s[8:9]
	s_cbranch_execz .LBB0_970
	v_lshl_add_u64 v[116:117], v[146:147], 2, s[54:55]
	s_waitcnt lgkmcnt(0)
	v_add_f32_e32 v112, v112, v113
	global_atomic_add_f32 v[116:117], v112, off
.LBB0_970:
	s_or_b64 exec, exec, s[2:3]
	v_or_b32_e32 v112, 16, v146
	s_waitcnt lgkmcnt(0)
	v_ashrrev_i32_e32 v113, 31, v112
	v_lshlrev_b64 v[116:117], 10, v[112:113]
	v_readlane_b32 s56, v246, 4
	v_lshl_add_u64 v[126:127], v[116:117], 0, v[144:145]
	v_readlane_b32 s57, v246, 5
	v_readlane_b32 s2, v246, 30
	v_readlane_b32 s3, v246, 31
	v_lshl_add_u64 v[156:157], v[126:127], 2, s[56:57]
	s_nop 1
	s_nop 1
	v_lshlrev_b64 v[126:127], 1, v[126:127]
	v_lshl_add_u64 v[158:159], s[2:3], 0, v[126:127]
	v_or_b32_e32 v126, 0x100, v126
	v_readlane_b32 s58, v246, 6
	v_readlane_b32 s59, v246, 7
	v_readlane_b32 s60, v246, 8
	v_readlane_b32 s61, v246, 9
	v_readlane_b32 s62, v246, 10
	v_readlane_b32 s63, v246, 11
	v_readlane_b32 s64, v246, 12
	v_readlane_b32 s65, v246, 13
	v_readlane_b32 s66, v246, 14
	v_readlane_b32 s67, v246, 15
	v_readlane_b32 s68, v246, 16
	v_readlane_b32 s69, v246, 17
	v_readlane_b32 s70, v246, 18
	v_readlane_b32 s71, v246, 19
	s_waitcnt vmcnt(8)
	v_mov_b32_e32 v116, v188
	v_mov_b32_e32 v117, v189
	v_mov_b32_e32 v118, v190
	v_mov_b32_e32 v119, v191
	v_mov_b32_e32 v122, v192
	v_mov_b32_e32 v123, v193
	v_mov_b32_e32 v124, v194
	v_mov_b32_e32 v125, v195
	global_load_dwordx4 v[188:191], v[252:253], off
	global_load_dwordx4 v[192:195], v[252:253], off offset:16
	v_pk_add_f32 v[118:119], v[110:111], v[118:119]
	v_pk_add_f32 v[116:117], v[108:109], v[116:117]
	v_pk_add_f32 v[124:125], v[106:107], v[124:125]
	v_pk_add_f32 v[122:123], v[104:105], v[122:123]
	v_cvt_pk_bf16_f32 v104, v116, v117
	v_cvt_pk_bf16_f32 v105, v118, v119
	v_mul_f32_e32 v115, v117, v117
	v_cvt_pk_bf16_f32 v106, v122, v123
	v_cvt_pk_bf16_f32 v107, v124, v125
	global_store_dwordx4 v[158:159], v[104:107], off
	s_nop 1
	s_nop 0
	s_nop 1
	v_mul_f32_e32 v117, v119, v119
	v_mul_f32_e32 v119, v123, v123
	v_fmac_f32_e32 v115, v116, v116
	v_fmac_f32_e32 v117, v118, v118
	v_mul_f32_e32 v121, v125, v125
	v_fmac_f32_e32 v119, v122, v122
	v_add_f32_e32 v115, v115, v117
	v_fmac_f32_e32 v121, v124, v124
	v_add_f32_e32 v115, v115, v119
	v_add_f32_e32 v115, v121, v115
	s_waitcnt vmcnt(9)
	v_mov_b32_e32 v104, v196
	v_mov_b32_e32 v105, v197
	v_mov_b32_e32 v106, v198
	v_mov_b32_e32 v107, v199
	v_mov_b32_e32 v108, v200
	v_mov_b32_e32 v109, v201
	v_mov_b32_e32 v110, v202
	v_mov_b32_e32 v111, v203
	global_load_dwordx4 v[196:199], v[252:253], off offset:512
	global_load_dwordx4 v[200:203], v[252:253], off offset:528
	s_mov_b64 s[96:97], 0x50000
	v_lshl_add_u64 v[252:253], v[252:253], 0, s[96:97]
	v_pk_add_f32 v[102:103], v[102:103], v[106:107]
	v_pk_add_f32 v[100:101], v[100:101], v[104:105]
	v_pk_add_f32 v[104:105], v[98:99], v[110:111]
	v_pk_add_f32 v[96:97], v[96:97], v[108:109]
	v_mul_f32_e32 v98, v101, v101
	v_mul_f32_e32 v99, v103, v103
	v_mul_f32_e32 v106, v97, v97
	v_fmac_f32_e32 v98, v100, v100
	v_fmac_f32_e32 v99, v102, v102
	v_mul_f32_e32 v107, v105, v105
	v_fmac_f32_e32 v106, v96, v96
	v_add_f32_e32 v98, v98, v99
	v_add_f32_e32 v98, v98, v106
	v_fmac_f32_e32 v107, v104, v104
	v_add_f32_e32 v98, v107, v98
	v_add_f32_e32 v106, v115, v98
	ds_bpermute_b32 v107, v120, v106
	v_cvt_pk_bf16_f32 v98, v100, v101
	v_cvt_pk_bf16_f32 v99, v102, v103
	v_cvt_pk_bf16_f32 v100, v96, v97
	v_lshl_add_u64 v[102:103], s[2:3], 0, v[126:127]
	s_waitcnt lgkmcnt(0)
	v_add_f32_e32 v96, v106, v107
	ds_bpermute_b32 v97, v114, v96
	v_cvt_pk_bf16_f32 v101, v104, v105
	global_store_dwordx4 v[102:103], v[98:101], off
	s_and_saveexec_b64 s[2:3], s[8:9]
	s_cbranch_execz .LBB0_972
	v_lshl_add_u64 v[98:99], v[112:113], 2, s[54:55]
	s_waitcnt lgkmcnt(0)
	v_add_f32_e32 v96, v96, v97
	global_atomic_add_f32 v[98:99], v96, off
.LBB0_972:
	s_or_b64 exec, exec, s[2:3]
	v_or_b32_e32 v96, 32, v146
	s_waitcnt lgkmcnt(0)
	v_ashrrev_i32_e32 v97, 31, v96
	v_lshlrev_b64 v[98:99], 10, v[96:97]
	v_readlane_b32 s56, v246, 4
	v_lshl_add_u64 v[106:107], v[98:99], 0, v[144:145]
	v_readlane_b32 s57, v246, 5
	v_readlane_b32 s2, v246, 30
	v_readlane_b32 s3, v246, 31
	v_lshl_add_u64 v[108:109], v[106:107], 2, s[56:57]
	s_nop 1
	s_nop 1
	v_lshlrev_b64 v[106:107], 1, v[106:107]
	v_lshl_add_u64 v[110:111], s[2:3], 0, v[106:107]
	v_or_b32_e32 v106, 0x100, v106
	v_readlane_b32 s58, v246, 6
	v_readlane_b32 s59, v246, 7
	v_readlane_b32 s60, v246, 8
	v_readlane_b32 s61, v246, 9
	v_readlane_b32 s62, v246, 10
	v_readlane_b32 s63, v246, 11
	v_readlane_b32 s64, v246, 12
	v_readlane_b32 s65, v246, 13
	v_readlane_b32 s66, v246, 14
	v_readlane_b32 s67, v246, 15
	v_readlane_b32 s68, v246, 16
	v_readlane_b32 s69, v246, 17
	v_readlane_b32 s70, v246, 18
	v_readlane_b32 s71, v246, 19
	s_waitcnt vmcnt(10)
	v_mov_b32_e32 v98, v172
	v_mov_b32_e32 v99, v173
	v_mov_b32_e32 v100, v174
	v_mov_b32_e32 v101, v175
	v_mov_b32_e32 v102, v176
	v_mov_b32_e32 v103, v177
	v_mov_b32_e32 v104, v178
	v_mov_b32_e32 v105, v179
	global_load_dwordx4 v[172:175], v[252:253], off
	global_load_dwordx4 v[176:179], v[252:253], off offset:16
	v_pk_add_f32 v[100:101], v[94:95], v[100:101]
	v_pk_add_f32 v[98:99], v[92:93], v[98:99]
	v_pk_add_f32 v[104:105], v[90:91], v[104:105]
	v_pk_add_f32 v[102:103], v[88:89], v[102:103]
	v_cvt_pk_bf16_f32 v88, v98, v99
	v_cvt_pk_bf16_f32 v89, v100, v101
	v_mul_f32_e32 v99, v99, v99
	v_cvt_pk_bf16_f32 v90, v102, v103
	v_cvt_pk_bf16_f32 v91, v104, v105
	global_store_dwordx4 v[110:111], v[88:91], off
	s_nop 1
	s_nop 0
	s_nop 1
	v_mul_f32_e32 v101, v101, v101
	v_mul_f32_e32 v103, v103, v103
	v_fmac_f32_e32 v99, v98, v98
	v_fmac_f32_e32 v101, v100, v100
	v_mul_f32_e32 v105, v105, v105
	v_fmac_f32_e32 v103, v102, v102
	v_add_f32_e32 v98, v99, v101
	v_fmac_f32_e32 v105, v104, v104
	v_add_f32_e32 v98, v98, v103
	v_add_f32_e32 v98, v105, v98
	s_waitcnt vmcnt(10)
	v_mov_b32_e32 v88, v180
	v_mov_b32_e32 v89, v181
	v_mov_b32_e32 v90, v182
	v_mov_b32_e32 v91, v183
	v_mov_b32_e32 v92, v184
	v_mov_b32_e32 v93, v185
	v_mov_b32_e32 v94, v186
	v_mov_b32_e32 v95, v187
	global_load_dwordx4 v[180:183], v[252:253], off offset:512
	global_load_dwordx4 v[184:187], v[252:253], off offset:528
	s_mov_b64 s[96:97], 0x10000
	v_lshl_add_u64 v[252:253], v[252:253], 0, s[96:97]
	v_pk_add_f32 v[86:87], v[86:87], v[90:91]
	v_pk_add_f32 v[84:85], v[84:85], v[88:89]
	v_pk_add_f32 v[88:89], v[82:83], v[94:95]
	v_pk_add_f32 v[80:81], v[80:81], v[92:93]
	v_mul_f32_e32 v82, v85, v85
	v_mul_f32_e32 v83, v87, v87
	v_mul_f32_e32 v90, v81, v81
	v_fmac_f32_e32 v82, v84, v84
	v_fmac_f32_e32 v83, v86, v86
	v_mul_f32_e32 v91, v89, v89
	v_fmac_f32_e32 v90, v80, v80
	v_add_f32_e32 v82, v82, v83
	v_add_f32_e32 v82, v82, v90
	v_fmac_f32_e32 v91, v88, v88
	v_add_f32_e32 v82, v91, v82
	v_add_f32_e32 v90, v98, v82
	ds_bpermute_b32 v91, v120, v90
	v_cvt_pk_bf16_f32 v82, v84, v85
	v_cvt_pk_bf16_f32 v83, v86, v87
	v_cvt_pk_bf16_f32 v84, v80, v81
	v_lshl_add_u64 v[86:87], s[2:3], 0, v[106:107]
	s_waitcnt lgkmcnt(0)
	v_add_f32_e32 v80, v90, v91
	ds_bpermute_b32 v81, v114, v80
	v_cvt_pk_bf16_f32 v85, v88, v89
	global_store_dwordx4 v[86:87], v[82:85], off
	s_and_saveexec_b64 s[2:3], s[8:9]
	s_cbranch_execz .LBB0_974
	v_lshl_add_u64 v[82:83], v[96:97], 2, s[54:55]
	s_waitcnt lgkmcnt(0)
	v_add_f32_e32 v80, v80, v81
	global_atomic_add_f32 v[82:83], v80, off
.LBB0_974:
	s_or_b64 exec, exec, s[2:3]
	v_or_b32_e32 v80, 48, v146
	s_waitcnt lgkmcnt(0)
	v_ashrrev_i32_e32 v81, 31, v80
	v_lshlrev_b64 v[82:83], 10, v[80:81]
	v_readlane_b32 s56, v246, 4
	v_lshl_add_u64 v[90:91], v[82:83], 0, v[144:145]
	v_readlane_b32 s57, v246, 5
	v_readlane_b32 s2, v246, 30
	v_readlane_b32 s3, v246, 31
	v_lshl_add_u64 v[92:93], v[90:91], 2, s[56:57]
	s_nop 1
	s_nop 1
	v_lshlrev_b64 v[90:91], 1, v[90:91]
	v_lshl_add_u64 v[94:95], s[2:3], 0, v[90:91]
	v_or_b32_e32 v90, 0x100, v90
	v_readlane_b32 s58, v246, 6
	v_readlane_b32 s59, v246, 7
	v_readlane_b32 s60, v246, 8
	v_readlane_b32 s61, v246, 9
	v_readlane_b32 s62, v246, 10
	v_readlane_b32 s63, v246, 11
	v_readlane_b32 s64, v246, 12
	v_readlane_b32 s65, v246, 13
	v_readlane_b32 s66, v246, 14
	v_readlane_b32 s67, v246, 15
	v_readlane_b32 s68, v246, 16
	v_readlane_b32 s69, v246, 17
	v_readlane_b32 s70, v246, 18
	v_readlane_b32 s71, v246, 19
	s_waitcnt vmcnt(10)
	v_mov_b32_e32 v82, v188
	v_mov_b32_e32 v83, v189
	v_mov_b32_e32 v84, v190
	v_mov_b32_e32 v85, v191
	v_mov_b32_e32 v86, v192
	v_mov_b32_e32 v87, v193
	v_mov_b32_e32 v88, v194
	v_mov_b32_e32 v89, v195
	global_load_dwordx4 v[188:191], v[252:253], off
	global_load_dwordx4 v[192:195], v[252:253], off offset:16
	v_pk_add_f32 v[84:85], v[78:79], v[84:85]
	v_pk_add_f32 v[82:83], v[76:77], v[82:83]
	v_pk_add_f32 v[88:89], v[74:75], v[88:89]
	v_pk_add_f32 v[86:87], v[72:73], v[86:87]
	v_cvt_pk_bf16_f32 v72, v82, v83
	v_cvt_pk_bf16_f32 v73, v84, v85
	v_mul_f32_e32 v83, v83, v83
	v_cvt_pk_bf16_f32 v74, v86, v87
	v_cvt_pk_bf16_f32 v75, v88, v89
	global_store_dwordx4 v[94:95], v[72:75], off
	s_nop 1
	s_nop 0
	s_nop 1
	v_mul_f32_e32 v85, v85, v85
	v_mul_f32_e32 v87, v87, v87
	v_fmac_f32_e32 v83, v82, v82
	v_fmac_f32_e32 v85, v84, v84
	v_mul_f32_e32 v89, v89, v89
	v_fmac_f32_e32 v87, v86, v86
	v_add_f32_e32 v82, v83, v85
	v_fmac_f32_e32 v89, v88, v88
	v_add_f32_e32 v82, v82, v87
	v_add_f32_e32 v82, v89, v82
	s_waitcnt vmcnt(10)
	v_mov_b32_e32 v72, v196
	v_mov_b32_e32 v73, v197
	v_mov_b32_e32 v74, v198
	v_mov_b32_e32 v75, v199
	v_mov_b32_e32 v76, v200
	v_mov_b32_e32 v77, v201
	v_mov_b32_e32 v78, v202
	v_mov_b32_e32 v79, v203
	global_load_dwordx4 v[196:199], v[252:253], off offset:512
	global_load_dwordx4 v[200:203], v[252:253], off offset:528
	s_mov_b64 s[96:97], 0x10000
	v_lshl_add_u64 v[252:253], v[252:253], 0, s[96:97]
	v_pk_add_f32 v[70:71], v[70:71], v[74:75]
	v_pk_add_f32 v[68:69], v[68:69], v[72:73]
	v_pk_add_f32 v[72:73], v[66:67], v[78:79]
	v_pk_add_f32 v[64:65], v[64:65], v[76:77]
	v_mul_f32_e32 v66, v69, v69
	v_mul_f32_e32 v67, v71, v71
	v_mul_f32_e32 v74, v65, v65
	v_fmac_f32_e32 v66, v68, v68
	v_fmac_f32_e32 v67, v70, v70
	v_mul_f32_e32 v75, v73, v73
	v_fmac_f32_e32 v74, v64, v64
	v_add_f32_e32 v66, v66, v67
	v_add_f32_e32 v66, v66, v74
	v_fmac_f32_e32 v75, v72, v72
	v_add_f32_e32 v66, v75, v66
	v_add_f32_e32 v74, v82, v66
	ds_bpermute_b32 v75, v120, v74
	v_cvt_pk_bf16_f32 v66, v68, v69
	v_cvt_pk_bf16_f32 v67, v70, v71
	v_cvt_pk_bf16_f32 v68, v64, v65
	v_lshl_add_u64 v[70:71], s[2:3], 0, v[90:91]
	s_waitcnt lgkmcnt(0)
	v_add_f32_e32 v64, v74, v75
	ds_bpermute_b32 v65, v114, v64
	v_cvt_pk_bf16_f32 v69, v72, v73
	global_store_dwordx4 v[70:71], v[66:69], off
	s_and_saveexec_b64 s[2:3], s[8:9]
	s_cbranch_execz .LBB0_976
	v_lshl_add_u64 v[66:67], v[80:81], 2, s[54:55]
	s_waitcnt lgkmcnt(0)
	v_add_f32_e32 v64, v64, v65
	global_atomic_add_f32 v[66:67], v64, off
.LBB0_976:
	s_or_b64 exec, exec, s[2:3]
	v_add_u32_e32 v64, 0x80, v146
	s_waitcnt lgkmcnt(0)
	v_ashrrev_i32_e32 v65, 31, v64
	v_lshlrev_b64 v[66:67], 10, v[64:65]
	v_readlane_b32 s56, v246, 4
	v_lshl_add_u64 v[74:75], v[66:67], 0, v[144:145]
	v_readlane_b32 s57, v246, 5
	v_readlane_b32 s2, v246, 30
	v_readlane_b32 s3, v246, 31
	v_lshl_add_u64 v[76:77], v[74:75], 2, s[56:57]
	s_nop 1
	s_nop 1
	v_lshlrev_b64 v[74:75], 1, v[74:75]
	v_lshl_add_u64 v[78:79], s[2:3], 0, v[74:75]
	v_or_b32_e32 v74, 0x100, v74
	v_readlane_b32 s58, v246, 6
	v_readlane_b32 s59, v246, 7
	v_readlane_b32 s60, v246, 8
	v_readlane_b32 s61, v246, 9
	v_readlane_b32 s62, v246, 10
	v_readlane_b32 s63, v246, 11
	v_readlane_b32 s64, v246, 12
	v_readlane_b32 s65, v246, 13
	v_readlane_b32 s66, v246, 14
	v_readlane_b32 s67, v246, 15
	v_readlane_b32 s68, v246, 16
	v_readlane_b32 s69, v246, 17
	v_readlane_b32 s70, v246, 18
	v_readlane_b32 s71, v246, 19
	s_waitcnt vmcnt(10)
	v_mov_b32_e32 v66, v172
	v_mov_b32_e32 v67, v173
	v_mov_b32_e32 v68, v174
	v_mov_b32_e32 v69, v175
	v_mov_b32_e32 v70, v176
	v_mov_b32_e32 v71, v177
	v_mov_b32_e32 v72, v178
	v_mov_b32_e32 v73, v179
	global_load_dwordx4 v[172:175], v[252:253], off
	global_load_dwordx4 v[176:179], v[252:253], off offset:16
	v_pk_add_f32 v[68:69], v[62:63], v[68:69]
	v_pk_add_f32 v[66:67], v[60:61], v[66:67]
	v_pk_add_f32 v[72:73], v[58:59], v[72:73]
	v_pk_add_f32 v[70:71], v[56:57], v[70:71]
	v_cvt_pk_bf16_f32 v56, v66, v67
	v_cvt_pk_bf16_f32 v57, v68, v69
	v_mul_f32_e32 v67, v67, v67
	v_cvt_pk_bf16_f32 v58, v70, v71
	v_cvt_pk_bf16_f32 v59, v72, v73
	global_store_dwordx4 v[78:79], v[56:59], off
	s_nop 1
	s_nop 0
	s_nop 1
	v_mul_f32_e32 v69, v69, v69
	v_mul_f32_e32 v71, v71, v71
	v_fmac_f32_e32 v67, v66, v66
	v_fmac_f32_e32 v69, v68, v68
	v_mul_f32_e32 v73, v73, v73
	v_fmac_f32_e32 v71, v70, v70
	v_add_f32_e32 v66, v67, v69
	v_fmac_f32_e32 v73, v72, v72
	v_add_f32_e32 v66, v66, v71
	v_add_f32_e32 v66, v73, v66
	s_waitcnt vmcnt(10)
	v_mov_b32_e32 v56, v180
	v_mov_b32_e32 v57, v181
	v_mov_b32_e32 v58, v182
	v_mov_b32_e32 v59, v183
	v_mov_b32_e32 v60, v184
	v_mov_b32_e32 v61, v185
	v_mov_b32_e32 v62, v186
	v_mov_b32_e32 v63, v187
	global_load_dwordx4 v[180:183], v[252:253], off offset:512
	global_load_dwordx4 v[184:187], v[252:253], off offset:528
	s_mov_b64 s[96:97], 0x10000
	v_lshl_add_u64 v[252:253], v[252:253], 0, s[96:97]
	v_pk_add_f32 v[54:55], v[54:55], v[58:59]
	v_pk_add_f32 v[52:53], v[52:53], v[56:57]
	v_pk_add_f32 v[56:57], v[50:51], v[62:63]
	v_pk_add_f32 v[48:49], v[48:49], v[60:61]
	v_mul_f32_e32 v50, v53, v53
	v_mul_f32_e32 v51, v55, v55
	v_mul_f32_e32 v58, v49, v49
	v_fmac_f32_e32 v50, v52, v52
	v_fmac_f32_e32 v51, v54, v54
	v_mul_f32_e32 v59, v57, v57
	v_fmac_f32_e32 v58, v48, v48
	v_add_f32_e32 v50, v50, v51
	v_add_f32_e32 v50, v50, v58
	v_fmac_f32_e32 v59, v56, v56
	v_add_f32_e32 v50, v59, v50
	v_add_f32_e32 v58, v66, v50
	ds_bpermute_b32 v59, v120, v58
	v_cvt_pk_bf16_f32 v50, v52, v53
	v_cvt_pk_bf16_f32 v51, v54, v55
	v_cvt_pk_bf16_f32 v52, v48, v49
	v_lshl_add_u64 v[54:55], s[2:3], 0, v[74:75]
	s_waitcnt lgkmcnt(0)
	v_add_f32_e32 v48, v58, v59
	ds_bpermute_b32 v49, v114, v48
	v_cvt_pk_bf16_f32 v53, v56, v57
	global_store_dwordx4 v[54:55], v[50:53], off
	s_and_saveexec_b64 s[2:3], s[8:9]
	s_cbranch_execz .LBB0_978
	v_lshl_add_u64 v[50:51], v[64:65], 2, s[54:55]
	s_waitcnt lgkmcnt(0)
	v_add_f32_e32 v48, v48, v49
	global_atomic_add_f32 v[50:51], v48, off
.LBB0_978:
	s_or_b64 exec, exec, s[2:3]
	v_add_u32_e32 v48, 0x90, v146
	s_waitcnt lgkmcnt(0)
	v_ashrrev_i32_e32 v49, 31, v48
	v_lshlrev_b64 v[50:51], 10, v[48:49]
	v_readlane_b32 s56, v246, 4
	v_lshl_add_u64 v[58:59], v[50:51], 0, v[144:145]
	v_readlane_b32 s57, v246, 5
	v_readlane_b32 s2, v246, 30
	v_readlane_b32 s3, v246, 31
	v_lshl_add_u64 v[60:61], v[58:59], 2, s[56:57]
	s_nop 1
	s_nop 1
	v_lshlrev_b64 v[58:59], 1, v[58:59]
	v_lshl_add_u64 v[62:63], s[2:3], 0, v[58:59]
	v_or_b32_e32 v58, 0x100, v58
	v_readlane_b32 s58, v246, 6
	v_readlane_b32 s59, v246, 7
	v_readlane_b32 s60, v246, 8
	v_readlane_b32 s61, v246, 9
	v_readlane_b32 s62, v246, 10
	v_readlane_b32 s63, v246, 11
	v_readlane_b32 s64, v246, 12
	v_readlane_b32 s65, v246, 13
	v_readlane_b32 s66, v246, 14
	v_readlane_b32 s67, v246, 15
	v_readlane_b32 s68, v246, 16
	v_readlane_b32 s69, v246, 17
	v_readlane_b32 s70, v246, 18
	v_readlane_b32 s71, v246, 19
	s_waitcnt vmcnt(10)
	v_mov_b32_e32 v50, v188
	v_mov_b32_e32 v51, v189
	v_mov_b32_e32 v52, v190
	v_mov_b32_e32 v53, v191
	v_mov_b32_e32 v54, v192
	v_mov_b32_e32 v55, v193
	v_mov_b32_e32 v56, v194
	v_mov_b32_e32 v57, v195
	global_load_dwordx4 v[188:191], v[252:253], off
	global_load_dwordx4 v[192:195], v[252:253], off offset:16
	v_pk_add_f32 v[52:53], v[46:47], v[52:53]
	v_pk_add_f32 v[50:51], v[44:45], v[50:51]
	v_pk_add_f32 v[56:57], v[42:43], v[56:57]
	v_pk_add_f32 v[54:55], v[40:41], v[54:55]
	v_cvt_pk_bf16_f32 v40, v50, v51
	v_cvt_pk_bf16_f32 v41, v52, v53
	v_mul_f32_e32 v51, v51, v51
	v_cvt_pk_bf16_f32 v42, v54, v55
	v_cvt_pk_bf16_f32 v43, v56, v57
	global_store_dwordx4 v[62:63], v[40:43], off
	s_nop 1
	s_nop 0
	s_nop 1
	v_mul_f32_e32 v53, v53, v53
	v_mul_f32_e32 v55, v55, v55
	v_fmac_f32_e32 v51, v50, v50
	v_fmac_f32_e32 v53, v52, v52
	v_mul_f32_e32 v57, v57, v57
	v_fmac_f32_e32 v55, v54, v54
	v_add_f32_e32 v50, v51, v53
	v_fmac_f32_e32 v57, v56, v56
	v_add_f32_e32 v50, v50, v55
	v_add_f32_e32 v50, v57, v50
	s_waitcnt vmcnt(10)
	v_mov_b32_e32 v40, v196
	v_mov_b32_e32 v41, v197
	v_mov_b32_e32 v42, v198
	v_mov_b32_e32 v43, v199
	v_mov_b32_e32 v44, v200
	v_mov_b32_e32 v45, v201
	v_mov_b32_e32 v46, v202
	v_mov_b32_e32 v47, v203
	global_load_dwordx4 v[196:199], v[252:253], off offset:512
	global_load_dwordx4 v[200:203], v[252:253], off offset:528
	v_pk_add_f32 v[38:39], v[38:39], v[42:43]
	v_pk_add_f32 v[36:37], v[36:37], v[40:41]
	v_pk_add_f32 v[40:41], v[34:35], v[46:47]
	v_pk_add_f32 v[32:33], v[32:33], v[44:45]
	v_mul_f32_e32 v34, v37, v37
	v_mul_f32_e32 v35, v39, v39
	v_mul_f32_e32 v42, v33, v33
	v_fmac_f32_e32 v34, v36, v36
	v_fmac_f32_e32 v35, v38, v38
	v_mul_f32_e32 v43, v41, v41
	v_fmac_f32_e32 v42, v32, v32
	v_add_f32_e32 v34, v34, v35
	v_add_f32_e32 v34, v34, v42
	v_fmac_f32_e32 v43, v40, v40
	v_add_f32_e32 v34, v43, v34
	v_add_f32_e32 v42, v50, v34
	ds_bpermute_b32 v43, v120, v42
	v_cvt_pk_bf16_f32 v34, v36, v37
	v_cvt_pk_bf16_f32 v35, v38, v39
	v_cvt_pk_bf16_f32 v36, v32, v33
	v_lshl_add_u64 v[38:39], s[2:3], 0, v[58:59]
	s_waitcnt lgkmcnt(0)
	v_add_f32_e32 v32, v42, v43
	ds_bpermute_b32 v33, v114, v32
	v_cvt_pk_bf16_f32 v37, v40, v41
	global_store_dwordx4 v[38:39], v[34:37], off
	s_and_saveexec_b64 s[2:3], s[8:9]
	s_cbranch_execz .LBB0_980
	v_lshl_add_u64 v[34:35], v[48:49], 2, s[54:55]
	s_waitcnt lgkmcnt(0)
	v_add_f32_e32 v32, v32, v33
	global_atomic_add_f32 v[34:35], v32, off
.LBB0_980:
	s_or_b64 exec, exec, s[2:3]
	v_add_u32_e32 v32, 0xa0, v146
	s_waitcnt lgkmcnt(0)
	v_ashrrev_i32_e32 v33, 31, v32
	v_lshlrev_b64 v[34:35], 10, v[32:33]
	v_readlane_b32 s56, v246, 4
	v_lshl_add_u64 v[42:43], v[34:35], 0, v[144:145]
	v_readlane_b32 s57, v246, 5
	v_readlane_b32 s2, v246, 30
	v_readlane_b32 s3, v246, 31
	v_lshl_add_u64 v[44:45], v[42:43], 2, s[56:57]
	s_nop 1
	s_nop 1
	v_lshlrev_b64 v[42:43], 1, v[42:43]
	v_lshl_add_u64 v[46:47], s[2:3], 0, v[42:43]
	v_or_b32_e32 v42, 0x100, v42
	v_readlane_b32 s58, v246, 6
	v_readlane_b32 s59, v246, 7
	v_readlane_b32 s60, v246, 8
	v_readlane_b32 s61, v246, 9
	v_readlane_b32 s62, v246, 10
	v_readlane_b32 s63, v246, 11
	v_readlane_b32 s64, v246, 12
	v_readlane_b32 s65, v246, 13
	v_readlane_b32 s66, v246, 14
	v_readlane_b32 s67, v246, 15
	v_readlane_b32 s68, v246, 16
	v_readlane_b32 s69, v246, 17
	v_readlane_b32 s70, v246, 18
	v_readlane_b32 s71, v246, 19
	s_waitcnt vmcnt(10)
	v_mov_b32_e32 v34, v172
	v_mov_b32_e32 v35, v173
	v_mov_b32_e32 v36, v174
	v_mov_b32_e32 v37, v175
	v_mov_b32_e32 v38, v176
	v_mov_b32_e32 v39, v177
	v_mov_b32_e32 v40, v178
	v_mov_b32_e32 v41, v179
	v_pk_add_f32 v[36:37], v[30:31], v[36:37]
	v_pk_add_f32 v[34:35], v[28:29], v[34:35]
	v_pk_add_f32 v[40:41], v[26:27], v[40:41]
	v_pk_add_f32 v[38:39], v[24:25], v[38:39]
	v_cvt_pk_bf16_f32 v24, v34, v35
	v_cvt_pk_bf16_f32 v25, v36, v37
	v_mul_f32_e32 v35, v35, v35
	v_cvt_pk_bf16_f32 v26, v38, v39
	v_cvt_pk_bf16_f32 v27, v40, v41
	global_store_dwordx4 v[46:47], v[24:27], off
	s_nop 1
	s_nop 0
	s_nop 1
	v_mul_f32_e32 v37, v37, v37
	v_mul_f32_e32 v39, v39, v39
	v_fmac_f32_e32 v35, v34, v34
	v_fmac_f32_e32 v37, v36, v36
	v_mul_f32_e32 v41, v41, v41
	v_fmac_f32_e32 v39, v38, v38
	v_add_f32_e32 v34, v35, v37
	v_fmac_f32_e32 v41, v40, v40
	v_add_f32_e32 v34, v34, v39
	v_add_f32_e32 v34, v41, v34
	s_waitcnt vmcnt(8)
	v_mov_b32_e32 v24, v180
	v_mov_b32_e32 v25, v181
	v_mov_b32_e32 v26, v182
	v_mov_b32_e32 v27, v183
	v_mov_b32_e32 v28, v184
	v_mov_b32_e32 v29, v185
	v_mov_b32_e32 v30, v186
	v_mov_b32_e32 v31, v187
	v_pk_add_f32 v[22:23], v[22:23], v[26:27]
	v_pk_add_f32 v[20:21], v[20:21], v[24:25]
	v_pk_add_f32 v[24:25], v[18:19], v[30:31]
	v_pk_add_f32 v[16:17], v[16:17], v[28:29]
	v_mul_f32_e32 v18, v21, v21
	v_mul_f32_e32 v19, v23, v23
	v_mul_f32_e32 v26, v17, v17
	v_fmac_f32_e32 v18, v20, v20
	v_fmac_f32_e32 v19, v22, v22
	v_mul_f32_e32 v27, v25, v25
	v_fmac_f32_e32 v26, v16, v16
	v_add_f32_e32 v18, v18, v19
	v_add_f32_e32 v18, v18, v26
	v_fmac_f32_e32 v27, v24, v24
	v_add_f32_e32 v18, v27, v18
	v_add_f32_e32 v26, v34, v18
	ds_bpermute_b32 v27, v120, v26
	v_cvt_pk_bf16_f32 v18, v20, v21
	v_cvt_pk_bf16_f32 v19, v22, v23
	v_cvt_pk_bf16_f32 v20, v16, v17
	v_lshl_add_u64 v[22:23], s[2:3], 0, v[42:43]
	s_waitcnt lgkmcnt(0)
	v_add_f32_e32 v16, v26, v27
	ds_bpermute_b32 v17, v114, v16
	v_cvt_pk_bf16_f32 v21, v24, v25
	global_store_dwordx4 v[22:23], v[18:21], off
	s_and_saveexec_b64 s[2:3], s[8:9]
	s_cbranch_execz .LBB0_982
	v_lshl_add_u64 v[18:19], v[32:33], 2, s[54:55]
	s_waitcnt lgkmcnt(0)
	v_add_f32_e32 v16, v16, v17
	global_atomic_add_f32 v[18:19], v16, off
.LBB0_982:
	s_or_b64 exec, exec, s[2:3]
	v_add_u32_e32 v16, 0xb0, v146
	s_waitcnt lgkmcnt(0)
	v_ashrrev_i32_e32 v17, 31, v16
	v_lshlrev_b64 v[18:19], 10, v[16:17]
	v_readlane_b32 s56, v246, 4
	v_lshl_add_u64 v[26:27], v[18:19], 0, v[144:145]
	v_readlane_b32 s57, v246, 5
	v_readlane_b32 s2, v246, 30
	v_readlane_b32 s3, v246, 31
	v_lshl_add_u64 v[28:29], v[26:27], 2, s[56:57]
	s_nop 1
	s_nop 1
	v_lshlrev_b64 v[26:27], 1, v[26:27]
	v_lshl_add_u64 v[30:31], s[2:3], 0, v[26:27]
	v_or_b32_e32 v26, 0x100, v26
	v_readlane_b32 s58, v246, 6
	v_readlane_b32 s59, v246, 7
	v_readlane_b32 s60, v246, 8
	v_readlane_b32 s61, v246, 9
	v_readlane_b32 s62, v246, 10
	v_readlane_b32 s63, v246, 11
	v_readlane_b32 s64, v246, 12
	v_readlane_b32 s65, v246, 13
	v_readlane_b32 s66, v246, 14
	v_readlane_b32 s67, v246, 15
	v_readlane_b32 s68, v246, 16
	v_readlane_b32 s69, v246, 17
	v_readlane_b32 s70, v246, 18
	v_readlane_b32 s71, v246, 19
	s_waitcnt vmcnt(6)
	v_mov_b32_e32 v18, v188
	v_mov_b32_e32 v19, v189
	v_mov_b32_e32 v20, v190
	v_mov_b32_e32 v21, v191
	v_mov_b32_e32 v22, v192
	v_mov_b32_e32 v23, v193
	v_mov_b32_e32 v24, v194
	v_mov_b32_e32 v25, v195
	v_pk_add_f32 v[20:21], v[14:15], v[20:21]
	v_pk_add_f32 v[18:19], v[12:13], v[18:19]
	v_pk_add_f32 v[24:25], v[10:11], v[24:25]
	v_pk_add_f32 v[22:23], v[8:9], v[22:23]
	v_cvt_pk_bf16_f32 v8, v18, v19
	v_cvt_pk_bf16_f32 v9, v20, v21
	v_mul_f32_e32 v19, v19, v19
	v_cvt_pk_bf16_f32 v10, v22, v23
	v_cvt_pk_bf16_f32 v11, v24, v25
	global_store_dwordx4 v[30:31], v[8:11], off
	s_nop 1
	s_nop 0
	s_nop 1
	v_mul_f32_e32 v21, v21, v21
	v_mul_f32_e32 v23, v23, v23
	v_fmac_f32_e32 v19, v18, v18
	v_fmac_f32_e32 v21, v20, v20
	v_mul_f32_e32 v25, v25, v25
	v_fmac_f32_e32 v23, v22, v22
	v_add_f32_e32 v18, v19, v21
	v_fmac_f32_e32 v25, v24, v24
	v_add_f32_e32 v18, v18, v23
	v_add_f32_e32 v18, v25, v18
	s_waitcnt vmcnt(4)
	v_mov_b32_e32 v8, v196
	v_mov_b32_e32 v9, v197
	v_mov_b32_e32 v10, v198
	v_mov_b32_e32 v11, v199
	v_mov_b32_e32 v12, v200
	v_mov_b32_e32 v13, v201
	v_mov_b32_e32 v14, v202
	v_mov_b32_e32 v15, v203
	v_pk_add_f32 v[6:7], v[6:7], v[10:11]
	v_pk_add_f32 v[4:5], v[4:5], v[8:9]
	v_pk_add_f32 v[8:9], v[2:3], v[14:15]
	v_pk_add_f32 v[0:1], v[0:1], v[12:13]
	v_mul_f32_e32 v2, v5, v5
	v_mul_f32_e32 v3, v7, v7
	v_mul_f32_e32 v10, v1, v1
	v_fmac_f32_e32 v2, v4, v4
	v_fmac_f32_e32 v3, v6, v6
	v_mul_f32_e32 v11, v9, v9
	v_fmac_f32_e32 v10, v0, v0
	v_add_f32_e32 v2, v2, v3
	v_add_f32_e32 v2, v2, v10
	v_fmac_f32_e32 v11, v8, v8
	v_add_f32_e32 v2, v11, v2
	v_add_f32_e32 v10, v18, v2
	ds_bpermute_b32 v11, v120, v10
	v_cvt_pk_bf16_f32 v2, v4, v5
	v_cvt_pk_bf16_f32 v3, v6, v7
	v_cvt_pk_bf16_f32 v4, v0, v1
	v_lshl_add_u64 v[6:7], s[2:3], 0, v[26:27]
	s_waitcnt lgkmcnt(0)
	v_add_f32_e32 v0, v10, v11
	ds_bpermute_b32 v1, v114, v0
	v_cvt_pk_bf16_f32 v5, v8, v9
	global_store_dwordx4 v[6:7], v[2:5], off
	s_and_saveexec_b64 s[2:3], s[8:9]
	s_cbranch_execz .LBB0_984
	v_lshl_add_u64 v[2:3], v[16:17], 2, s[54:55]
	s_waitcnt lgkmcnt(0)
	v_add_f32_e32 v0, v0, v1
	global_atomic_add_f32 v[2:3], v0, off

.LBB0_1132:
	v_lshl_add_u32 v148, s54, 8, v150
	v_lshl_or_b32 v146, s55, 8, v152
	v_ashrrev_i32_e32 v149, 31, v148
	v_ashrrev_i32_e32 v147, 31, v146
	v_lshlrev_b64 v[144:145], 10, v[148:149]
	v_lshl_add_u64 v[144:145], v[144:145], 0, v[146:147]
	v_readlane_b32 s2, v246, 30
	v_lshlrev_b64 v[144:145], 1, v[144:145]
	v_readlane_b32 s3, v246, 31
	v_or_b32_e32 v160, 0x100, v144
	v_mov_b32_e32 v161, v145
	v_lshl_add_u64 v[156:157], s[2:3], 0, v[144:145]
	v_mov_b32_e32 v252, v156
	v_mov_b32_e32 v253, v157
	s_mov_b64 s[68:69], 0x8000
	s_mov_b64 s[70:71], 0x28000
	global_load_dwordx4 v[168:171], v[252:253], off
	global_load_dwordx4 v[172:175], v[252:253], off offset:256
	v_lshl_add_u64 v[252:253], v[252:253], 0, s[68:69]
	global_load_dwordx4 v[176:179], v[252:253], off
	global_load_dwordx4 v[180:183], v[252:253], off offset:256
	v_lshl_add_u64 v[252:253], v[252:253], 0, s[68:69]
	global_load_dwordx4 v[184:187], v[252:253], off
	global_load_dwordx4 v[188:191], v[252:253], off offset:256
	v_lshl_add_u64 v[252:253], v[252:253], 0, s[68:69]
	global_load_dwordx4 v[192:195], v[252:253], off
	global_load_dwordx4 v[196:199], v[252:253], off offset:256
	v_lshl_add_u64 v[252:253], v[252:253], 0, s[70:71]
	s_nop 1
	v_lshl_add_u64 v[162:163], s[2:3], 0, v[160:161]
	v_lshl_add_u64 v[160:161], s[88:89], 0, v[160:161]
	s_and_b64 vcc, exec, s[4:5]
	s_waitcnt vmcnt(7)
	v_mov_b32_e32 v156, v168
	v_mov_b32_e32 v157, v169
	v_mov_b32_e32 v158, v170
	v_mov_b32_e32 v159, v171
	global_load_dwordx4 v[168:171], v[252:253], off
	v_lshlrev_b32_e32 v149, 16, v156
	v_and_b32_e32 v156, 0xffff0000, v156
	v_lshlrev_b32_e32 v164, 16, v157
	v_and_b32_e32 v157, 0xffff0000, v157
	v_lshlrev_b32_e32 v166, 16, v159
	v_and_b32_e32 v159, 0xffff0000, v159
	v_lshlrev_b32_e32 v165, 16, v158
	v_and_b32_e32 v158, 0xffff0000, v158
	v_add_f32_e32 v124, v124, v149
	v_add_f32_e32 v125, v125, v156
	v_add_f32_e32 v126, v126, v164
	v_add_f32_e32 v127, v127, v157
	v_add_f32_e32 v123, v123, v159
	v_add_f32_e32 v149, v120, v165
	v_add_f32_e32 v156, v121, v158
	v_add_f32_e32 v157, v122, v166
	v_cvt_pk_bf16_f32 v120, v124, v125
	v_cvt_pk_bf16_f32 v121, v126, v127
	v_cvt_pk_bf16_f32 v122, v149, v156
	v_cvt_pk_bf16_f32 v123, v157, v123
	s_nop 1
	v_or_b32_e32 v156, 16, v148
	v_ashrrev_i32_e32 v157, 31, v156
	v_lshlrev_b64 v[156:157], 10, v[156:157]
	v_lshl_add_u64 v[158:159], s[88:89], 0, v[144:145]
	v_lshl_add_u64 v[156:157], v[156:157], 0, v[146:147]
	global_store_dwordx4 v[158:159], v[120:123], off
	v_lshlrev_b64 v[156:157], 1, v[156:157]
	v_lshl_add_u64 v[162:163], s[2:3], 0, v[156:157]
	s_waitcnt vmcnt(8)
	v_mov_b32_e32 v124, v172
	v_mov_b32_e32 v125, v173
	v_mov_b32_e32 v126, v174
	v_mov_b32_e32 v127, v175
	global_load_dwordx4 v[172:175], v[252:253], off offset:256
	v_lshl_add_u64 v[252:253], v[252:253], 0, s[68:69]
	v_lshlrev_b32_e32 v120, 16, v124
	v_and_b32_e32 v121, 0xffff0000, v124
	v_lshlrev_b32_e32 v122, 16, v125
	v_and_b32_e32 v123, 0xffff0000, v125
	v_lshlrev_b32_e32 v124, 16, v126
	v_and_b32_e32 v125, 0xffff0000, v126
	v_lshlrev_b32_e32 v126, 16, v127
	v_and_b32_e32 v127, 0xffff0000, v127
	v_add_f32_e32 v115, v115, v127
	v_add_f32_e32 v116, v116, v120
	v_add_f32_e32 v117, v117, v121
	v_add_f32_e32 v118, v118, v122
	v_add_f32_e32 v119, v119, v123
	v_add_f32_e32 v120, v112, v124
	v_add_f32_e32 v121, v113, v125
	v_add_f32_e32 v122, v114, v126
	v_cvt_pk_bf16_f32 v112, v116, v117
	v_cvt_pk_bf16_f32 v113, v118, v119
	v_cvt_pk_bf16_f32 v114, v120, v121
	v_cvt_pk_bf16_f32 v115, v122, v115
	global_store_dwordx4 v[160:161], v[112:115], off
	s_nop 1
	v_lshl_add_u64 v[116:117], s[88:89], 0, v[156:157]
	v_or_b32_e32 v156, 0x100, v156
	v_lshl_add_u64 v[118:119], s[2:3], 0, v[156:157]
	s_waitcnt vmcnt(9)
	v_mov_b32_e32 v112, v176
	v_mov_b32_e32 v113, v177
	v_mov_b32_e32 v114, v178
	v_mov_b32_e32 v115, v179
	global_load_dwordx4 v[176:179], v[252:253], off
	v_lshlrev_b32_e32 v120, 16, v112
	v_and_b32_e32 v112, 0xffff0000, v112
	v_lshlrev_b32_e32 v121, 16, v113
	v_and_b32_e32 v113, 0xffff0000, v113
	v_lshlrev_b32_e32 v123, 16, v115
	v_and_b32_e32 v115, 0xffff0000, v115
	v_lshlrev_b32_e32 v122, 16, v114
	v_and_b32_e32 v114, 0xffff0000, v114
	v_add_f32_e32 v108, v108, v120
	v_add_f32_e32 v109, v109, v112
	v_add_f32_e32 v110, v110, v121
	v_add_f32_e32 v111, v111, v113
	v_add_f32_e32 v107, v107, v115
	v_add_f32_e32 v112, v104, v122
	v_add_f32_e32 v113, v105, v114
	v_add_f32_e32 v114, v106, v123
	v_cvt_pk_bf16_f32 v104, v108, v109
	v_cvt_pk_bf16_f32 v105, v110, v111
	v_cvt_pk_bf16_f32 v106, v112, v113
	v_cvt_pk_bf16_f32 v107, v114, v107
	s_nop 1
	v_or_b32_e32 v112, 32, v148
	v_ashrrev_i32_e32 v113, 31, v112
	v_lshlrev_b64 v[112:113], 10, v[112:113]
	v_lshl_add_u64 v[112:113], v[112:113], 0, v[146:147]
	global_store_dwordx4 v[116:117], v[104:107], off
	v_lshlrev_b64 v[112:113], 1, v[112:113]
	v_lshl_add_u64 v[118:119], s[88:89], 0, v[156:157]
	v_lshl_add_u64 v[114:115], s[2:3], 0, v[112:113]
	s_waitcnt vmcnt(10)
	v_mov_b32_e32 v108, v180
	v_mov_b32_e32 v109, v181
	v_mov_b32_e32 v110, v182
	v_mov_b32_e32 v111, v183
	global_load_dwordx4 v[180:183], v[252:253], off offset:256
	v_lshl_add_u64 v[252:253], v[252:253], 0, s[68:69]
	v_lshlrev_b32_e32 v104, 16, v108
	v_and_b32_e32 v105, 0xffff0000, v108
	v_lshlrev_b32_e32 v106, 16, v109
	v_and_b32_e32 v107, 0xffff0000, v109
	v_lshlrev_b32_e32 v108, 16, v110
	v_and_b32_e32 v109, 0xffff0000, v110
	v_lshlrev_b32_e32 v110, 16, v111
	v_and_b32_e32 v111, 0xffff0000, v111
	v_add_f32_e32 v99, v99, v111
	v_add_f32_e32 v100, v100, v104
	v_add_f32_e32 v101, v101, v105
	v_add_f32_e32 v102, v102, v106
	v_add_f32_e32 v103, v103, v107
	v_add_f32_e32 v104, v96, v108
	v_add_f32_e32 v105, v97, v109
	v_add_f32_e32 v106, v98, v110
	v_cvt_pk_bf16_f32 v96, v100, v101
	v_cvt_pk_bf16_f32 v97, v102, v103
	v_cvt_pk_bf16_f32 v98, v104, v105
	v_cvt_pk_bf16_f32 v99, v106, v99
	global_store_dwordx4 v[118:119], v[96:99], off
	s_nop 1
	v_lshl_add_u64 v[100:101], s[88:89], 0, v[112:113]
	v_or_b32_e32 v112, 0x100, v112
	v_lshl_add_u64 v[102:103], s[2:3], 0, v[112:113]
	s_waitcnt vmcnt(11)
	v_mov_b32_e32 v96, v184
	v_mov_b32_e32 v97, v185
	v_mov_b32_e32 v98, v186
	v_mov_b32_e32 v99, v187
	global_load_dwordx4 v[184:187], v[252:253], off
	v_lshlrev_b32_e32 v104, 16, v96
	v_and_b32_e32 v96, 0xffff0000, v96
	v_lshlrev_b32_e32 v105, 16, v97
	v_and_b32_e32 v97, 0xffff0000, v97
	v_lshlrev_b32_e32 v107, 16, v99
	v_and_b32_e32 v99, 0xffff0000, v99
	v_lshlrev_b32_e32 v106, 16, v98
	v_and_b32_e32 v98, 0xffff0000, v98
	v_add_f32_e32 v92, v92, v104
	v_add_f32_e32 v93, v93, v96
	v_add_f32_e32 v94, v94, v105
	v_add_f32_e32 v95, v95, v97
	v_add_f32_e32 v91, v91, v99
	v_add_f32_e32 v96, v88, v106
	v_add_f32_e32 v97, v89, v98
	v_add_f32_e32 v98, v90, v107
	v_cvt_pk_bf16_f32 v88, v92, v93
	v_cvt_pk_bf16_f32 v89, v94, v95
	v_cvt_pk_bf16_f32 v90, v96, v97
	v_cvt_pk_bf16_f32 v91, v98, v91
	s_nop 1
	v_or_b32_e32 v96, 48, v148
	v_ashrrev_i32_e32 v97, 31, v96
	v_lshlrev_b64 v[96:97], 10, v[96:97]
	v_lshl_add_u64 v[96:97], v[96:97], 0, v[146:147]
	global_store_dwordx4 v[100:101], v[88:91], off
	v_lshlrev_b64 v[96:97], 1, v[96:97]
	v_lshl_add_u64 v[102:103], s[88:89], 0, v[112:113]
	v_lshl_add_u64 v[98:99], s[2:3], 0, v[96:97]
	s_waitcnt vmcnt(12)
	v_mov_b32_e32 v92, v188
	v_mov_b32_e32 v93, v189
	v_mov_b32_e32 v94, v190
	v_mov_b32_e32 v95, v191
	global_load_dwordx4 v[188:191], v[252:253], off offset:256
	v_lshl_add_u64 v[252:253], v[252:253], 0, s[68:69]
	v_lshlrev_b32_e32 v88, 16, v92
	v_and_b32_e32 v89, 0xffff0000, v92
	v_lshlrev_b32_e32 v90, 16, v93
	v_and_b32_e32 v91, 0xffff0000, v93
	v_lshlrev_b32_e32 v92, 16, v94
	v_and_b32_e32 v93, 0xffff0000, v94
	v_lshlrev_b32_e32 v94, 16, v95
	v_and_b32_e32 v95, 0xffff0000, v95
	v_add_f32_e32 v83, v83, v95
	v_add_f32_e32 v84, v84, v88
	v_add_f32_e32 v85, v85, v89
	v_add_f32_e32 v86, v86, v90
	v_add_f32_e32 v87, v87, v91
	v_add_f32_e32 v88, v80, v92
	v_add_f32_e32 v89, v81, v93
	v_add_f32_e32 v90, v82, v94
	v_cvt_pk_bf16_f32 v80, v84, v85
	v_cvt_pk_bf16_f32 v81, v86, v87
	v_cvt_pk_bf16_f32 v82, v88, v89
	v_cvt_pk_bf16_f32 v83, v90, v83
	global_store_dwordx4 v[102:103], v[80:83], off
	s_nop 1
	v_lshl_add_u64 v[84:85], s[88:89], 0, v[96:97]
	v_or_b32_e32 v96, 0x100, v96
	v_lshl_add_u64 v[86:87], s[2:3], 0, v[96:97]
	s_waitcnt vmcnt(13)
	v_mov_b32_e32 v80, v192
	v_mov_b32_e32 v81, v193
	v_mov_b32_e32 v82, v194
	v_mov_b32_e32 v83, v195
	global_load_dwordx4 v[192:195], v[252:253], off
	v_lshlrev_b32_e32 v88, 16, v80
	v_and_b32_e32 v80, 0xffff0000, v80
	v_lshlrev_b32_e32 v89, 16, v81
	v_and_b32_e32 v81, 0xffff0000, v81
	v_lshlrev_b32_e32 v91, 16, v83
	v_and_b32_e32 v83, 0xffff0000, v83
	v_lshlrev_b32_e32 v90, 16, v82
	v_and_b32_e32 v82, 0xffff0000, v82
	v_add_f32_e32 v76, v76, v88
	v_add_f32_e32 v77, v77, v80
	v_add_f32_e32 v78, v78, v89
	v_add_f32_e32 v79, v79, v81
	v_add_f32_e32 v75, v75, v83
	v_add_f32_e32 v80, v72, v90
	v_add_f32_e32 v81, v73, v82
	v_add_f32_e32 v82, v74, v91
	v_cvt_pk_bf16_f32 v72, v76, v77
	v_cvt_pk_bf16_f32 v73, v78, v79
	v_cvt_pk_bf16_f32 v74, v80, v81
	v_cvt_pk_bf16_f32 v75, v82, v75
	s_nop 1
	v_lshl_add_u64 v[80:81], v[144:145], 0, s[12:13]
	global_store_dwordx4 v[84:85], v[72:75], off
	v_lshl_add_u64 v[86:87], s[88:89], 0, v[96:97]
	v_lshl_add_u64 v[82:83], s[2:3], 0, v[80:81]
	s_waitcnt vmcnt(14)
	v_mov_b32_e32 v76, v196
	v_mov_b32_e32 v77, v197
	v_mov_b32_e32 v78, v198
	v_mov_b32_e32 v79, v199
	global_load_dwordx4 v[196:199], v[252:253], off offset:256
	v_lshlrev_b32_e32 v72, 16, v76
	v_and_b32_e32 v73, 0xffff0000, v76
	v_lshlrev_b32_e32 v74, 16, v77
	v_and_b32_e32 v75, 0xffff0000, v77
	v_lshlrev_b32_e32 v76, 16, v78
	v_and_b32_e32 v77, 0xffff0000, v78
	v_lshlrev_b32_e32 v78, 16, v79
	v_and_b32_e32 v79, 0xffff0000, v79
	v_add_f32_e32 v67, v67, v79
	v_add_f32_e32 v68, v68, v72
	v_add_f32_e32 v69, v69, v73
	v_add_f32_e32 v70, v70, v74
	v_add_f32_e32 v71, v71, v75
	v_add_f32_e32 v72, v64, v76
	v_add_f32_e32 v73, v65, v77
	v_add_f32_e32 v74, v66, v78
	v_cvt_pk_bf16_f32 v64, v68, v69
	v_cvt_pk_bf16_f32 v65, v70, v71
	v_cvt_pk_bf16_f32 v66, v72, v73
	v_cvt_pk_bf16_f32 v67, v74, v67
	global_store_dwordx4 v[86:87], v[64:67], off
	s_nop 1
	v_lshl_add_u64 v[68:69], v[144:145], 0, s[14:15]
	v_lshl_add_u64 v[70:71], s[2:3], 0, v[68:69]
	v_lshl_add_u64 v[68:69], s[88:89], 0, v[68:69]
	s_waitcnt vmcnt(15)
	v_mov_b32_e32 v64, v168
	v_mov_b32_e32 v65, v169
	v_mov_b32_e32 v66, v170
	v_mov_b32_e32 v67, v171
	v_lshlrev_b32_e32 v72, 16, v64
	v_and_b32_e32 v64, 0xffff0000, v64
	v_lshlrev_b32_e32 v73, 16, v65
	v_and_b32_e32 v65, 0xffff0000, v65
	v_lshlrev_b32_e32 v75, 16, v67
	v_and_b32_e32 v67, 0xffff0000, v67
	v_lshlrev_b32_e32 v74, 16, v66
	v_and_b32_e32 v66, 0xffff0000, v66
	v_add_f32_e32 v60, v60, v72
	v_add_f32_e32 v61, v61, v64
	v_add_f32_e32 v62, v62, v73
	v_add_f32_e32 v63, v63, v65
	v_add_f32_e32 v59, v59, v67
	v_add_f32_e32 v64, v56, v74
	v_add_f32_e32 v65, v57, v66
	v_add_f32_e32 v66, v58, v75
	v_cvt_pk_bf16_f32 v56, v60, v61
	v_cvt_pk_bf16_f32 v57, v62, v63
	v_cvt_pk_bf16_f32 v58, v64, v65
	v_cvt_pk_bf16_f32 v59, v66, v59
	s_nop 1
	v_lshl_add_u64 v[66:67], s[88:89], 0, v[80:81]
	global_store_dwordx4 v[66:67], v[56:59], off
	v_lshl_add_u64 v[64:65], v[144:145], 0, s[16:17]
	v_lshl_add_u64 v[70:71], s[2:3], 0, v[64:65]
	s_waitcnt vmcnt(14)
	v_mov_b32_e32 v60, v172
	v_mov_b32_e32 v61, v173
	v_mov_b32_e32 v62, v174
	v_mov_b32_e32 v63, v175
	v_lshlrev_b32_e32 v56, 16, v60
	v_and_b32_e32 v57, 0xffff0000, v60
	v_lshlrev_b32_e32 v58, 16, v61
	v_and_b32_e32 v59, 0xffff0000, v61
	v_lshlrev_b32_e32 v60, 16, v62
	v_and_b32_e32 v61, 0xffff0000, v62
	v_lshlrev_b32_e32 v62, 16, v63
	v_and_b32_e32 v63, 0xffff0000, v63
	v_add_f32_e32 v51, v51, v63
	v_add_f32_e32 v52, v52, v56
	v_add_f32_e32 v53, v53, v57
	v_add_f32_e32 v54, v54, v58
	v_add_f32_e32 v55, v55, v59
	v_add_f32_e32 v56, v48, v60
	v_add_f32_e32 v57, v49, v61
	v_add_f32_e32 v58, v50, v62
	v_cvt_pk_bf16_f32 v48, v52, v53
	v_cvt_pk_bf16_f32 v49, v54, v55
	v_cvt_pk_bf16_f32 v50, v56, v57
	v_cvt_pk_bf16_f32 v51, v58, v51
	global_store_dwordx4 v[68:69], v[48:51], off
	s_nop 1
	v_lshl_add_u64 v[52:53], v[144:145], 0, s[18:19]
	v_lshl_add_u64 v[54:55], s[2:3], 0, v[52:53]
	v_lshl_add_u64 v[52:53], s[88:89], 0, v[52:53]
	s_waitcnt vmcnt(13)
	v_mov_b32_e32 v48, v176
	v_mov_b32_e32 v49, v177
	v_mov_b32_e32 v50, v178
	v_mov_b32_e32 v51, v179
	v_lshlrev_b32_e32 v56, 16, v48
	v_and_b32_e32 v48, 0xffff0000, v48
	v_lshlrev_b32_e32 v57, 16, v49
	v_and_b32_e32 v49, 0xffff0000, v49
	v_lshlrev_b32_e32 v59, 16, v51
	v_and_b32_e32 v51, 0xffff0000, v51
	v_lshlrev_b32_e32 v58, 16, v50
	v_and_b32_e32 v50, 0xffff0000, v50
	v_add_f32_e32 v44, v44, v56
	v_add_f32_e32 v45, v45, v48
	v_add_f32_e32 v46, v46, v57
	v_add_f32_e32 v47, v47, v49
	v_add_f32_e32 v43, v43, v51
	v_add_f32_e32 v48, v40, v58
	v_add_f32_e32 v49, v41, v50
	v_add_f32_e32 v50, v42, v59
	v_cvt_pk_bf16_f32 v40, v44, v45
	v_cvt_pk_bf16_f32 v41, v46, v47
	v_cvt_pk_bf16_f32 v42, v48, v49
	v_cvt_pk_bf16_f32 v43, v50, v43
	s_nop 1
	v_lshl_add_u64 v[50:51], s[88:89], 0, v[64:65]
	global_store_dwordx4 v[50:51], v[40:43], off
	v_lshl_add_u64 v[48:49], v[144:145], 0, s[20:21]
	v_lshl_add_u64 v[54:55], s[2:3], 0, v[48:49]
	s_waitcnt vmcnt(12)
	v_mov_b32_e32 v44, v180
	v_mov_b32_e32 v45, v181
	v_mov_b32_e32 v46, v182
	v_mov_b32_e32 v47, v183
	v_lshlrev_b32_e32 v40, 16, v44
	v_and_b32_e32 v41, 0xffff0000, v44
	v_lshlrev_b32_e32 v42, 16, v45
	v_and_b32_e32 v43, 0xffff0000, v45
	v_lshlrev_b32_e32 v44, 16, v46
	v_and_b32_e32 v45, 0xffff0000, v46
	v_lshlrev_b32_e32 v46, 16, v47
	v_and_b32_e32 v47, 0xffff0000, v47
	v_add_f32_e32 v35, v35, v47
	v_add_f32_e32 v36, v36, v40
	v_add_f32_e32 v37, v37, v41
	v_add_f32_e32 v38, v38, v42
	v_add_f32_e32 v39, v39, v43
	v_add_f32_e32 v40, v32, v44
	v_add_f32_e32 v41, v33, v45
	v_add_f32_e32 v42, v34, v46
	v_cvt_pk_bf16_f32 v32, v36, v37
	v_cvt_pk_bf16_f32 v33, v38, v39
	v_cvt_pk_bf16_f32 v34, v40, v41
	v_cvt_pk_bf16_f32 v35, v42, v35
	global_store_dwordx4 v[52:53], v[32:35], off
	s_nop 1
	v_lshl_add_u64 v[36:37], v[144:145], 0, s[22:23]
	v_lshl_add_u64 v[38:39], s[2:3], 0, v[36:37]
	v_lshl_add_u64 v[36:37], s[88:89], 0, v[36:37]
	s_waitcnt vmcnt(11)
	v_mov_b32_e32 v32, v184
	v_mov_b32_e32 v33, v185
	v_mov_b32_e32 v34, v186
	v_mov_b32_e32 v35, v187
	v_lshlrev_b32_e32 v40, 16, v32
	v_and_b32_e32 v32, 0xffff0000, v32
	v_lshlrev_b32_e32 v41, 16, v33
	v_and_b32_e32 v33, 0xffff0000, v33
	v_lshlrev_b32_e32 v43, 16, v35
	v_and_b32_e32 v35, 0xffff0000, v35
	v_lshlrev_b32_e32 v42, 16, v34
	v_and_b32_e32 v34, 0xffff0000, v34
	v_add_f32_e32 v28, v28, v40
	v_add_f32_e32 v29, v29, v32
	v_add_f32_e32 v30, v30, v41
	v_add_f32_e32 v31, v31, v33
	v_add_f32_e32 v27, v27, v35
	v_add_f32_e32 v32, v24, v42
	v_add_f32_e32 v33, v25, v34
	v_add_f32_e32 v34, v26, v43
	v_cvt_pk_bf16_f32 v24, v28, v29
	v_cvt_pk_bf16_f32 v25, v30, v31
	v_cvt_pk_bf16_f32 v26, v32, v33
	v_cvt_pk_bf16_f32 v27, v34, v27
	s_nop 1
	v_lshl_add_u64 v[34:35], s[88:89], 0, v[48:49]
	global_store_dwordx4 v[34:35], v[24:27], off
	v_lshl_add_u64 v[32:33], v[144:145], 0, s[24:25]
	v_lshl_add_u64 v[38:39], s[2:3], 0, v[32:33]
	s_waitcnt vmcnt(10)
	v_mov_b32_e32 v28, v188
	v_mov_b32_e32 v29, v189
	v_mov_b32_e32 v30, v190
	v_mov_b32_e32 v31, v191
	v_lshlrev_b32_e32 v24, 16, v28
	v_and_b32_e32 v25, 0xffff0000, v28
	v_lshlrev_b32_e32 v26, 16, v29
	v_and_b32_e32 v27, 0xffff0000, v29
	v_lshlrev_b32_e32 v28, 16, v30
	v_and_b32_e32 v29, 0xffff0000, v30
	v_lshlrev_b32_e32 v30, 16, v31
	v_and_b32_e32 v31, 0xffff0000, v31
	v_add_f32_e32 v19, v19, v31
	v_add_f32_e32 v20, v20, v24
	v_add_f32_e32 v21, v21, v25
	v_add_f32_e32 v22, v22, v26
	v_add_f32_e32 v23, v23, v27
	v_add_f32_e32 v24, v16, v28
	v_add_f32_e32 v25, v17, v29
	v_add_f32_e32 v26, v18, v30
	v_cvt_pk_bf16_f32 v16, v20, v21
	v_cvt_pk_bf16_f32 v17, v22, v23
	v_cvt_pk_bf16_f32 v18, v24, v25
	v_cvt_pk_bf16_f32 v19, v26, v19
	global_store_dwordx4 v[36:37], v[16:19], off
	s_nop 1
	v_lshl_add_u64 v[20:21], v[144:145], 0, s[26:27]
	v_lshl_add_u64 v[22:23], s[2:3], 0, v[20:21]
	s_mov_b64 s[2:3], -1
	s_waitcnt vmcnt(9)
	v_mov_b32_e32 v16, v192
	v_mov_b32_e32 v17, v193
	v_mov_b32_e32 v18, v194
	v_mov_b32_e32 v19, v195
	v_lshlrev_b32_e32 v24, 16, v16
	v_and_b32_e32 v16, 0xffff0000, v16
	v_lshlrev_b32_e32 v25, 16, v17
	v_and_b32_e32 v17, 0xffff0000, v17
	v_lshlrev_b32_e32 v27, 16, v19
	v_and_b32_e32 v19, 0xffff0000, v19
	v_lshlrev_b32_e32 v26, 16, v18
	v_and_b32_e32 v18, 0xffff0000, v18
	v_add_f32_e32 v12, v12, v24
	v_add_f32_e32 v13, v13, v16
	v_add_f32_e32 v14, v14, v25
	v_add_f32_e32 v15, v15, v17
	v_add_f32_e32 v11, v11, v19
	v_add_f32_e32 v16, v8, v26
	v_add_f32_e32 v17, v9, v18
	v_add_f32_e32 v18, v10, v27
	v_cvt_pk_bf16_f32 v8, v12, v13
	v_cvt_pk_bf16_f32 v9, v14, v15
	v_cvt_pk_bf16_f32 v10, v16, v17
	v_cvt_pk_bf16_f32 v11, v18, v11
	s_nop 1
	v_lshl_add_u64 v[16:17], s[88:89], 0, v[32:33]
	global_store_dwordx4 v[16:17], v[8:11], off
	v_lshl_add_u64 v[18:19], s[88:89], 0, v[20:21]
	s_waitcnt vmcnt(8)
	v_mov_b32_e32 v12, v196
	v_mov_b32_e32 v13, v197
	v_mov_b32_e32 v14, v198
	v_mov_b32_e32 v15, v199
	v_lshlrev_b32_e32 v8, 16, v12
	v_and_b32_e32 v9, 0xffff0000, v12
	v_lshlrev_b32_e32 v10, 16, v13
	v_and_b32_e32 v11, 0xffff0000, v13
	v_lshlrev_b32_e32 v12, 16, v14
	v_and_b32_e32 v13, 0xffff0000, v14
	v_lshlrev_b32_e32 v14, 16, v15
	v_and_b32_e32 v15, 0xffff0000, v15
	v_add_f32_e32 v3, v3, v15
	v_add_f32_e32 v4, v4, v8
	v_add_f32_e32 v5, v5, v9
	v_add_f32_e32 v6, v6, v10
	v_add_f32_e32 v7, v7, v11
	v_add_f32_e32 v8, v0, v12
	v_add_f32_e32 v9, v1, v13
	v_add_f32_e32 v10, v2, v14
	v_cvt_pk_bf16_f32 v0, v4, v5
	v_cvt_pk_bf16_f32 v1, v6, v7
	v_cvt_pk_bf16_f32 v2, v8, v9
	v_cvt_pk_bf16_f32 v3, v10, v3
	global_store_dwordx4 v[18:19], v[0:3], off
	s_cbranch_vccnz .LBB0_1117
	s_andn2_b64 vcc, exec, s[0:1]
	s_cbranch_vccnz .LBB0_1116
	s_barrier
	s_branch .LBB0_1116
